# prep phase: the eight waves of a workgroup combine their key maxima through LDS, one atomic max per workgroup and key kind
# speedup vs baseline: 1.0124x; 1.0072x over previous
; DI void phase_prep(const Args& a, int layer, LAS unsigned char* lds) {
;     ...
;         for (int it = gw; it < 6 * 4 * 256; it += NGW) {
;             const int which = it / 1024, bg = (it / 256) & 3, st = it & 255, b = bg >> 1, g = bg & 1;
;             if (which >= 3) {
;                 const int srccol = (which == 3 ? C_KS : which == 4 ? C_KW : C_KB) + g * 64;
;                 bf16_t* dst = (bf16_t*)(ws + (which == 3 ? WS_KSF : which == 4 ? WS_KWF : WS_KBF)) + (size_t)bg * 64 * S + (size_t)st * 4096;
;                 float rmax = 0.f;
; #pragma unroll
;                 for (int i = 0; i < 8; ++i) { const int tok = i * 8 + (lane >> 3), q = lane & 7;
;                     const u32x4 v = *(const u32x4*)(P + (size_t)(b * S + st * 64 + tok) * NP + srccol + q * 8);
.LBB0_340:
	s_and_b64 vcc, exec, s[0:1]
	s_cbranch_vccz .LBB0_406
	v_mov_b32_e32 v42, v185
	v_readlane_b32 s0, v252, 34
	v_ashrrev_i32_e32 v44, 6, v42
	v_and_b32_e32 v15, 31, v42
	v_add_u32_e32 v14, s0, v44
	s_movk_i32 s0, 0x17ff
	v_cmp_lt_i32_e32 vcc, s0, v14
	s_and_saveexec_b64 s[0:1], vcc
	s_xor_b64 s[0:1], exec, s[0:1]
	v_and_b32_e32 v128, 31, v42
	s_or_saveexec_b64 s[24:25], s[0:1]
	v_readlane_b32 s0, v252, 5
	v_readlane_b32 s1, v252, 6
	s_load_dword s19, s[0:1], 0x0
	v_and_b32_e32 v45, 63, v42
	v_lshlrev_b32_e32 v43, 5, v42
	s_waitcnt lgkmcnt(0)
	s_lshl_b32 s27, s19, 3
	s_xor_b64 exec, exec, s[24:25]
	s_cbranch_execz .LBB0_353
	s_movk_i32 s0, 0x2400
	v_lshrrev_b32_e32 v3, 3, v42
	v_mul_lo_u32 v0, v44, s0
	v_lshlrev_b32_e32 v1, 4, v42
	v_and_b32_e32 v18, 4, v3
	v_lshrrev_b32_e32 v3, 2, v42
	v_add_u32_e32 v16, 0, v0
	v_lshrrev_b32_e32 v17, 3, v45
	v_and_b32_e32 v128, 0x70, v1
	v_and_b32_e32 v20, 12, v3
	v_and_b32_e32 v3, 7, v42
	v_lshl_add_u64 v[4:5], s[30:31], 0, v[128:129]
	v_add_u32_e32 v2, v16, v128
	v_lshlrev_b32_e32 v128, 4, v3
	v_and_b32_e32 v3, 48, v1
	v_readlane_b32 s0, v255, 12
	v_or_b32_e32 v24, 24, v17
	s_waitcnt vmcnt(0)
	v_bitop3_b32 v37, v1, 48, 64 bitop3:0xe0
	s_lshl_b32 s8, s0, 4
	v_and_b32_e32 v9, 64, v1
	v_or_b32_e32 v1, v37, v17
	v_and_or_b32 v10, v24, 15, v3
	s_movk_i32 s0, 0x80
	v_and_b32_e32 v21, 0xe0, v43
	v_or_b32_e32 v28, 56, v17
	v_or_b32_e32 v39, 0x80, v1
	v_or3_b32 v41, v10, v9, s0
	v_bitop3_b32 v10, v17, 23, 48 bitop3:0xc8
	s_movk_i32 s0, 0x100
	v_or_b32_e32 v48, 0x180, v1
	v_bitop3_b32 v1, v17, 31, 56 bitop3:0xc8
	v_lshlrev_b32_e32 v0, 3, v45
	v_and_b32_e32 v19, 15, v42
	v_mul_u32_u24_e32 v8, 0x90, v17
	v_or_b32_e32 v23, 16, v17
	v_or3_b32 v47, v21, v10, s0
	v_or3_b32 v49, v21, v1, s0
	v_and_or_b32 v1, v28, 15, v3
	s_movk_i32 s0, 0x180
	v_lshl_add_u64 v[6:7], s[30:31], 0, v[128:129]
	v_cmp_eq_u32_e32 vcc, 0, v45
	s_add_i32 s8, s8, -12
	v_or_b32_e32 v22, 8, v17
	v_or_b32_e32 v25, 32, v17
	v_or_b32_e32 v26, 40, v17
	v_or_b32_e32 v27, 48, v17
	v_or_b32_e32 v29, 32, v15
	v_or_b32_e32 v30, 16, v19
	v_or_b32_e32 v31, 16, v18
	v_or_b32_e32 v32, 32, v19
	v_or_b32_e32 v33, 48, v19
	v_or_b32_e32 v34, 32, v18
	v_or_b32_e32 v35, 16, v20
	v_or_b32_e32 v36, 48, v18
	v_or_b32_e32 v38, v21, v23
	v_or_b32_e32 v40, v21, v24
	v_bitop3_b32 v46, v17, 15, 40 bitop3:0xc8
	v_or3_b32 v50, v1, v9, s0
	s_mov_b64 s[40:41], 0
	v_add_u32_e32 v51, v2, v8
	v_lshlrev_b32_e32 v8, 1, v0
	v_mov_b32_e32 v52, v14
	v_readlane_b32 s1, v255, 13
	v_readfirstlane_b32 s101, v14
	s_nop 1
	s_cmp_lt_u32 s101, 0x400
	s_movk_i32 s100, 0x13ff
	s_movk_i32 s101, 0x400
	s_cselect_b32 s100, 0x17ff, s100
	s_cselect_b32 s101, 0x1400, s101
	s_mov_b32 s44, 0x20000
	s_branch .LBB0_347

; DI void phase_prep(const Args& a, int layer, LAS unsigned char* lds) {
;     ...
;             if (which >= 3) {
;                 const int srccol = (which == 3 ? C_KS : which == 4 ? C_KW : C_KB) + g * 64;
;                 bf16_t* dst = (bf16_t*)(ws + (which == 3 ? WS_KSF : which == 4 ? WS_KWF : WS_KBF)) + (size_t)bg * 64 * S + (size_t)st * 4096;
;                 float rmax = 0.f;
; #pragma unroll
;                 for (int i = 0; i < 8; ++i) { const int tok = i * 8 + (lane >> 3), q = lane & 7;
;                     const u32x4 v = *(const u32x4*)(P + (size_t)(b * S + st * 64 + tok) * NP + srccol + q * 8);
;                     const int pos = which == 3 ? (((tok >> 4) * 2 + (q >> 2)) * 64 + (q & 3) * 16 + (tok & 15))
;                                                : ((tok >> 5) * 256 + (q >> 1) * 64 + (q & 1) * 32 + (tok & 31));
;                     *(u32x4*)(dst + pos * 8) = v;
;                     float ss = bflo(v.x) * bflo(v.x) + bfhi(v.x) * bfhi(v.x) + bflo(v.y) * bflo(v.y) + bfhi(v.y) * bfhi(v.y)
;                              + bflo(v.z) * bflo(v.z) + bfhi(v.z) * bfhi(v.z) + bflo(v.w) * bflo(v.w) + bfhi(v.w) * bfhi(v.w);
;                     ss += __shfl_xor(ss, 1); ss += __shfl_xor(ss, 2); ss += __shfl_xor(ss, 4);
;                     rmax = fmaxf(rmax, ss); }
.LBB0_349:
	s_andn2_saveexec_b64 s[42:43], s[42:43]
	s_cbranch_execz .LBB0_346
	v_and_b32_e32 v1, 0x7ffffc00, v52
	s_movk_i32 s0, 0xc00
	v_cmp_eq_u32_e64 s[38:39], s0, v1
	v_cmp_eq_u32_e64 s[0:1], s26, v1
	v_mov_b32_e32 v3, v129
	v_cndmask_b32_e64 v59, v21, v37, s[38:39]
	v_cndmask_b32_e64 v1, v208, v209, s[0:1]
	v_cndmask_b32_e64 v13, v1, v210, s[38:39]
	v_cndmask_b32_e64 v1, v211, v212, s[0:1]
	v_cndmask_b32_e64 v128, v1, v213, s[38:39]
	v_lshl_add_u64 v[10:11], s[98:99], 0, v[128:129]
	v_lshl_add_u64 v[2:3], v[10:11], 0, v[2:3]
	v_mov_b32_e32 v1, v129
	v_lshl_add_u64 v[10:11], v[2:3], 0, v[0:1]
	v_and_b32_e32 v3, 64, v197
	v_xor_b32_e32 v2, 1, v197
	v_add_u32_e32 v54, 64, v3
	v_cmp_lt_i32_e64 s[0:1], v2, v54
	v_lshlrev_b32_e32 v0, 1, v13
	v_lshl_or_b32 v128, v12, 7, v0
	v_cndmask_b32_e64 v2, v197, v2, s[0:1]
	v_lshlrev_b32_e32 v57, 2, v2
	v_xor_b32_e32 v2, 2, v197
	v_cmp_lt_i32_e64 s[0:1], v2, v54
	v_lshl_add_u64 v[0:1], v[6:7], 0, v[128:129]
	v_or_b32_e32 v68, v58, v17
	v_mul_u32_u24_e32 v68, 0xd00, v68
	v_lshlrev_b32_e32 v68, 1, v68
	v_mov_b32_e32 v69, v129
	v_lshl_add_u64 v[68:69], v[0:1], 0, v[68:69]
	global_load_dwordx4 v[70:73], v[68:69], off
	v_or_b32_e32 v68, v58, v22
	v_mul_u32_u24_e32 v68, 0xd00, v68
	v_lshlrev_b32_e32 v68, 1, v68
	v_mov_b32_e32 v69, v129
	v_lshl_add_u64 v[68:69], v[0:1], 0, v[68:69]
	global_load_dwordx4 v[74:77], v[68:69], off
	v_or_b32_e32 v68, v58, v23
	v_mul_u32_u24_e32 v68, 0xd00, v68
	v_lshlrev_b32_e32 v68, 1, v68
	v_mov_b32_e32 v69, v129
	v_lshl_add_u64 v[68:69], v[0:1], 0, v[68:69]
	global_load_dwordx4 v[78:81], v[68:69], off
	v_or_b32_e32 v68, v58, v24
	v_mul_u32_u24_e32 v68, 0xd00, v68
	v_lshlrev_b32_e32 v68, 1, v68
	v_mov_b32_e32 v69, v129
	v_lshl_add_u64 v[68:69], v[0:1], 0, v[68:69]
	global_load_dwordx4 v[82:85], v[68:69], off
	v_or_b32_e32 v68, v58, v25
	v_mul_u32_u24_e32 v68, 0xd00, v68
	v_lshlrev_b32_e32 v68, 1, v68
	v_mov_b32_e32 v69, v129
	v_lshl_add_u64 v[68:69], v[0:1], 0, v[68:69]
	global_load_dwordx4 v[86:89], v[68:69], off
	v_or_b32_e32 v68, v58, v26
	v_mul_u32_u24_e32 v68, 0xd00, v68
	v_lshlrev_b32_e32 v68, 1, v68
	v_mov_b32_e32 v69, v129
	v_lshl_add_u64 v[68:69], v[0:1], 0, v[68:69]
	global_load_dwordx4 v[90:93], v[68:69], off
	v_or_b32_e32 v68, v58, v27
	v_mul_u32_u24_e32 v68, 0xd00, v68
	v_lshlrev_b32_e32 v68, 1, v68
	v_mov_b32_e32 v69, v129
	v_lshl_add_u64 v[68:69], v[0:1], 0, v[68:69]
	global_load_dwordx4 v[94:97], v[68:69], off
	v_or_b32_e32 v68, v58, v28
	v_mul_u32_u24_e32 v68, 0xd00, v68
	v_lshlrev_b32_e32 v68, 1, v68
	v_mov_b32_e32 v69, v129
	v_lshl_add_u64 v[68:69], v[0:1], 0, v[68:69]
	global_load_dwordx4 v[98:101], v[68:69], off
	s_waitcnt vmcnt(0)
	v_or_b32_e32 v12, v59, v17
	v_cndmask_b32_e64 v2, v197, v2, s[0:1]
	v_lshlrev_b32_e32 v56, 2, v2
	v_xor_b32_e32 v2, 4, v197
	v_cmp_lt_i32_e64 s[0:1], v2, v54
	s_nop 1
	v_cndmask_b32_e64 v2, v197, v2, s[0:1]
	v_lshlrev_b32_e32 v55, 2, v2
	v_or_b32_e32 v2, v58, v17
	v_mul_u32_u24_e32 v2, 0xd00, v2
	v_lshlrev_b32_e32 v128, 1, v2
	v_lshl_add_u64 v[2:3], v[0:1], 0, v[128:129]
	v_mov_b64_e32 v[60:61], v[70:71]
	v_mov_b64_e32 v[62:63], v[72:73]
	v_lshlrev_b32_e32 v128, 4, v12
	v_lshl_add_u64 v[12:13], v[10:11], 0, v[128:129]
	s_mov_b32 s0, 0x34000
	v_add_co_u32_e64 v2, s[0:1], s0, v2
	global_store_dwordx4 v[12:13], v[60:63], off
	v_lshlrev_b32_e32 v64, 16, v60
	s_nop 0
	v_and_b32_e32 v60, 0xffff0000, v60
	v_mul_f32_e32 v60, v60, v60
	v_fmac_f32_e32 v60, v64, v64
	v_lshlrev_b32_e32 v64, 16, v61
	v_fmac_f32_e32 v60, v64, v64
	v_and_b32_e32 v61, 0xffff0000, v61
	v_fmac_f32_e32 v60, v61, v61
	v_lshlrev_b32_e32 v61, 16, v62
	v_fmac_f32_e32 v60, v61, v61
	v_and_b32_e32 v61, 0xffff0000, v62
	v_fmac_f32_e32 v60, v61, v61
	v_lshlrev_b32_e32 v61, 16, v63
	v_fmac_f32_e32 v60, v61, v61
	v_and_b32_e32 v61, 0xffff0000, v63
	v_fmac_f32_e32 v60, v61, v61
	ds_bpermute_b32 v61, v57, v60
	v_or_b32_e32 v64, v59, v22
	v_addc_co_u32_e64 v3, s[0:1], 0, v3, s[0:1]
	s_waitcnt lgkmcnt(0)
	v_add_f32_e32 v60, v60, v61
	ds_bpermute_b32 v61, v56, v60
	s_waitcnt lgkmcnt(0)
	v_add_f32_e32 v60, v60, v61
	ds_bpermute_b32 v61, v55, v60
	s_waitcnt lgkmcnt(0)
	v_add_f32_e32 v66, v60, v61
	v_or_b32_e32 v60, v58, v22
	v_mul_u32_u24_e32 v60, 0xd00, v60
	v_lshlrev_b32_e32 v128, 1, v60
	v_lshl_add_u64 v[60:61], v[0:1], 0, v[128:129]
	v_mov_b64_e32 v[60:61], v[74:75]
	v_mov_b64_e32 v[62:63], v[76:77]
	v_lshlrev_b32_e32 v128, 4, v64
	v_lshl_add_u64 v[64:65], v[10:11], 0, v[128:129]
	global_store_dwordx4 v[64:65], v[60:63], off
	v_lshlrev_b32_e32 v64, 16, v60
	s_nop 0
	v_and_b32_e32 v60, 0xffff0000, v60
	v_mul_f32_e32 v60, v60, v60
	v_fmac_f32_e32 v60, v64, v64
	v_lshlrev_b32_e32 v64, 16, v61
	v_fmac_f32_e32 v60, v64, v64
	v_and_b32_e32 v61, 0xffff0000, v61
	v_fmac_f32_e32 v60, v61, v61
	v_lshlrev_b32_e32 v61, 16, v62
	v_fmac_f32_e32 v60, v61, v61
	v_and_b32_e32 v61, 0xffff0000, v62
	v_fmac_f32_e32 v60, v61, v61
	v_lshlrev_b32_e32 v61, 16, v63
	v_fmac_f32_e32 v60, v61, v61
	v_and_b32_e32 v61, 0xffff0000, v63
	v_fmac_f32_e32 v60, v61, v61
	ds_bpermute_b32 v61, v57, v60
	v_cndmask_b32_e64 v64, v38, v39, s[38:39]
	s_waitcnt lgkmcnt(0)
	v_add_f32_e32 v60, v60, v61
	ds_bpermute_b32 v61, v56, v60
	s_waitcnt lgkmcnt(0)
	v_add_f32_e32 v60, v60, v61
	ds_bpermute_b32 v61, v55, v60
	s_waitcnt lgkmcnt(0)
; DI void phase_prep(const Args& a, int layer, LAS unsigned char* lds) {
;     ...
;                 for (int i = 0; i < 8; ++i) { const int tok = i * 8 + (lane >> 3), q = lane & 7;
;                     const u32x4 v = *(const u32x4*)(P + (size_t)(b * S + st * 64 + tok) * NP + srccol + q * 8);
;                     const int pos = which == 3 ? (((tok >> 4) * 2 + (q >> 2)) * 64 + (q & 3) * 16 + (tok & 15))
;                                                : ((tok >> 5) * 256 + (q >> 1) * 64 + (q & 1) * 32 + (tok & 31));
;                     *(u32x4*)(dst + pos * 8) = v;
;                     float ss = bflo(v.x) * bflo(v.x) + bfhi(v.x) * bfhi(v.x) + bflo(v.y) * bflo(v.y) + bfhi(v.y) * bfhi(v.y)
;                              + bflo(v.z) * bflo(v.z) + bfhi(v.z) * bfhi(v.z) + bflo(v.w) * bflo(v.w) + bfhi(v.w) * bfhi(v.w);
;                     ss += __shfl_xor(ss, 1); ss += __shfl_xor(ss, 2); ss += __shfl_xor(ss, 4);
;                     rmax = fmaxf(rmax, ss); }
	v_add_f32_e32 v60, v60, v61
	v_max3_f32 v66, v66, 0, v60
	v_or_b32_e32 v60, v58, v23
	v_mul_u32_u24_e32 v60, 0xd00, v60
	v_lshlrev_b32_e32 v128, 1, v60
	v_lshl_add_u64 v[60:61], v[0:1], 0, v[128:129]
	v_mov_b64_e32 v[60:61], v[78:79]
	v_mov_b64_e32 v[62:63], v[80:81]
	v_lshlrev_b32_e32 v128, 4, v64
	v_lshl_add_u64 v[64:65], v[10:11], 0, v[128:129]
	global_store_dwordx4 v[64:65], v[60:63], off
	v_lshlrev_b32_e32 v64, 16, v60
	s_nop 0
	v_and_b32_e32 v60, 0xffff0000, v60
	v_mul_f32_e32 v60, v60, v60
	v_fmac_f32_e32 v60, v64, v64
	v_lshlrev_b32_e32 v64, 16, v61
	v_fmac_f32_e32 v60, v64, v64
	v_and_b32_e32 v61, 0xffff0000, v61
	v_fmac_f32_e32 v60, v61, v61
	v_lshlrev_b32_e32 v61, 16, v62
	v_fmac_f32_e32 v60, v61, v61
	v_and_b32_e32 v61, 0xffff0000, v62
	v_fmac_f32_e32 v60, v61, v61
	v_lshlrev_b32_e32 v61, 16, v63
	v_fmac_f32_e32 v60, v61, v61
	v_and_b32_e32 v61, 0xffff0000, v63
	v_fmac_f32_e32 v60, v61, v61
	ds_bpermute_b32 v61, v57, v60
	v_cndmask_b32_e64 v64, v40, v41, s[38:39]
	s_waitcnt lgkmcnt(0)
	v_add_f32_e32 v60, v60, v61
	ds_bpermute_b32 v61, v56, v60
	s_waitcnt lgkmcnt(0)
	v_add_f32_e32 v60, v60, v61
	ds_bpermute_b32 v61, v55, v60
	s_waitcnt lgkmcnt(0)
	v_add_f32_e32 v67, v60, v61
	v_or_b32_e32 v60, v58, v24
	v_mul_u32_u24_e32 v60, 0xd00, v60
	v_lshlrev_b32_e32 v128, 1, v60
	v_lshl_add_u64 v[60:61], v[0:1], 0, v[128:129]
	v_mov_b64_e32 v[60:61], v[82:83]
	v_mov_b64_e32 v[62:63], v[84:85]
	v_lshlrev_b32_e32 v128, 4, v64
	v_lshl_add_u64 v[64:65], v[10:11], 0, v[128:129]
	global_store_dwordx4 v[64:65], v[60:63], off
	v_lshlrev_b32_e32 v64, 16, v60
	s_nop 0
	v_and_b32_e32 v60, 0xffff0000, v60
	v_mul_f32_e32 v60, v60, v60
	v_fmac_f32_e32 v60, v64, v64
	v_lshlrev_b32_e32 v64, 16, v61
	v_fmac_f32_e32 v60, v64, v64
	v_and_b32_e32 v61, 0xffff0000, v61
	v_fmac_f32_e32 v60, v61, v61
	v_lshlrev_b32_e32 v61, 16, v62
	v_fmac_f32_e32 v60, v61, v61
	v_and_b32_e32 v61, 0xffff0000, v62
	v_fmac_f32_e32 v60, v61, v61
	v_lshlrev_b32_e32 v61, 16, v63
	v_fmac_f32_e32 v60, v61, v61
	v_and_b32_e32 v61, 0xffff0000, v63
	v_mov_b64_e32 v[62:63], v[86:87]
	v_mov_b64_e32 v[64:65], v[88:89]
	v_add_co_u32_e64 v2, s[0:1], s26, v12
	v_fmac_f32_e32 v60, v61, v61
	s_nop 0
	v_addc_co_u32_e64 v3, s[0:1], 0, v13, s[0:1]
	ds_bpermute_b32 v61, v57, v60
	s_waitcnt lgkmcnt(0)
	v_add_f32_e32 v60, v60, v61
	ds_bpermute_b32 v61, v56, v60
	s_waitcnt lgkmcnt(0)
	v_add_f32_e32 v60, v60, v61
	ds_bpermute_b32 v61, v55, v60
	s_waitcnt lgkmcnt(0)
	v_add_f32_e32 v60, v60, v61
	v_max3_f32 v60, v66, v67, v60
	global_store_dwordx4 v[2:3], v[62:65], off
	v_and_b32_e32 v3, 0xffff0000, v62
	v_lshlrev_b32_e32 v2, 16, v62
	v_mul_f32_e32 v3, v3, v3
	v_fmac_f32_e32 v3, v2, v2
	v_lshlrev_b32_e32 v2, 16, v63
	v_fmac_f32_e32 v3, v2, v2
	v_and_b32_e32 v2, 0xffff0000, v63
	v_fmac_f32_e32 v3, v2, v2
	v_lshlrev_b32_e32 v2, 16, v64
	v_fmac_f32_e32 v3, v2, v2
	v_and_b32_e32 v2, 0xffff0000, v64
	v_fmac_f32_e32 v3, v2, v2
	v_lshlrev_b32_e32 v2, 16, v65
	v_fmac_f32_e32 v3, v2, v2
	v_and_b32_e32 v2, 0xffff0000, v65
	v_fmac_f32_e32 v3, v2, v2
	ds_bpermute_b32 v2, v57, v3
	s_waitcnt lgkmcnt(0)
	v_add_f32_e32 v2, v3, v2
	ds_bpermute_b32 v3, v56, v2
	s_waitcnt lgkmcnt(0)
	v_add_f32_e32 v2, v2, v3
	ds_bpermute_b32 v3, v55, v2
	s_waitcnt lgkmcnt(0)
	v_add_f32_e32 v12, v2, v3
	v_or_b32_e32 v2, v58, v26
	v_mul_u32_u24_e32 v2, 0xd00, v2
	v_lshlrev_b32_e32 v128, 1, v2
	v_lshl_add_u64 v[2:3], v[0:1], 0, v[128:129]
	v_mov_b64_e32 v[62:63], v[90:91]
	v_mov_b64_e32 v[64:65], v[92:93]
	v_or_b32_e32 v2, v59, v46
	v_lshlrev_b32_e32 v128, 4, v2
	v_lshl_add_u64 v[2:3], v[10:11], 0, v[128:129]
	v_add_co_u32_e64 v2, s[0:1], s26, v2
	s_nop 1
	v_addc_co_u32_e64 v3, s[0:1], 0, v3, s[0:1]
	global_store_dwordx4 v[2:3], v[62:65], off
	v_and_b32_e32 v3, 0xffff0000, v62
	v_lshlrev_b32_e32 v2, 16, v62
	v_mul_f32_e32 v3, v3, v3
	v_fmac_f32_e32 v3, v2, v2
	v_lshlrev_b32_e32 v2, 16, v63
	v_fmac_f32_e32 v3, v2, v2
	v_and_b32_e32 v2, 0xffff0000, v63
	v_fmac_f32_e32 v3, v2, v2
	v_lshlrev_b32_e32 v2, 16, v64
	v_fmac_f32_e32 v3, v2, v2
	v_and_b32_e32 v2, 0xffff0000, v64
	v_fmac_f32_e32 v3, v2, v2
	v_lshlrev_b32_e32 v2, 16, v65
	v_fmac_f32_e32 v3, v2, v2
	v_and_b32_e32 v2, 0xffff0000, v65
	v_fmac_f32_e32 v3, v2, v2
	ds_bpermute_b32 v2, v57, v3
	s_waitcnt lgkmcnt(0)
; DI void phase_prep(const Args& a, int layer, LAS unsigned char* lds) {
;     ...
;                 for (int i = 0; i < 8; ++i) { const int tok = i * 8 + (lane >> 3), q = lane & 7;
;                     const u32x4 v = *(const u32x4*)(P + (size_t)(b * S + st * 64 + tok) * NP + srccol + q * 8);
;                     const int pos = which == 3 ? (((tok >> 4) * 2 + (q >> 2)) * 64 + (q & 3) * 16 + (tok & 15))
;                                                : ((tok >> 5) * 256 + (q >> 1) * 64 + (q & 1) * 32 + (tok & 31));
;                     *(u32x4*)(dst + pos * 8) = v;
;                     float ss = bflo(v.x) * bflo(v.x) + bfhi(v.x) * bfhi(v.x) + bflo(v.y) * bflo(v.y) + bfhi(v.y) * bfhi(v.y)
;                              + bflo(v.z) * bflo(v.z) + bfhi(v.z) * bfhi(v.z) + bflo(v.w) * bflo(v.w) + bfhi(v.w) * bfhi(v.w);
;                     ss += __shfl_xor(ss, 1); ss += __shfl_xor(ss, 2); ss += __shfl_xor(ss, 4);
;                     rmax = fmaxf(rmax, ss); }
;                 rmax = fmaxf(rmax, __shfl_xor(rmax, 8)); rmax = fmaxf(rmax, __shfl_xor(rmax, 16)); rmax = fmaxf(rmax, __shfl_xor(rmax, 32));
;                 if (lane == 0) atomicMax((unsigned*)(ws + WS_KMAX) + (layer * 4 + (which - 3)) * 4 + bg, __builtin_bit_cast(unsigned, rmax));
	v_add_f32_e32 v2, v3, v2
	ds_bpermute_b32 v3, v56, v2
	s_waitcnt lgkmcnt(0)
	v_add_f32_e32 v2, v2, v3
	ds_bpermute_b32 v3, v55, v2
	s_waitcnt lgkmcnt(0)
	v_add_f32_e32 v2, v2, v3
	v_max3_f32 v12, v60, v12, v2
	v_or_b32_e32 v2, v58, v27
	v_mul_u32_u24_e32 v2, 0xd00, v2
	v_lshlrev_b32_e32 v128, 1, v2
	v_lshl_add_u64 v[2:3], v[0:1], 0, v[128:129]
	v_mov_b64_e32 v[60:61], v[94:95]
	v_mov_b64_e32 v[62:63], v[96:97]
	v_cndmask_b32_e64 v2, v47, v48, s[38:39]
	v_lshlrev_b32_e32 v128, 4, v2
	v_lshl_add_u64 v[2:3], v[10:11], 0, v[128:129]
	global_store_dwordx4 v[2:3], v[60:63], off
	v_and_b32_e32 v3, 0xffff0000, v60
	v_lshlrev_b32_e32 v2, 16, v60
	v_mul_f32_e32 v3, v3, v3
	v_fmac_f32_e32 v3, v2, v2
	v_lshlrev_b32_e32 v2, 16, v61
	v_fmac_f32_e32 v3, v2, v2
	v_and_b32_e32 v2, 0xffff0000, v61
	v_fmac_f32_e32 v3, v2, v2
	v_lshlrev_b32_e32 v2, 16, v62
	v_fmac_f32_e32 v3, v2, v2
	v_and_b32_e32 v2, 0xffff0000, v62
	v_fmac_f32_e32 v3, v2, v2
	v_lshlrev_b32_e32 v2, 16, v63
	v_fmac_f32_e32 v3, v2, v2
	v_and_b32_e32 v2, 0xffff0000, v63
	v_fmac_f32_e32 v3, v2, v2
	ds_bpermute_b32 v2, v57, v3
	s_waitcnt lgkmcnt(0)
	v_add_f32_e32 v2, v3, v2
	ds_bpermute_b32 v3, v56, v2
	s_waitcnt lgkmcnt(0)
	v_add_f32_e32 v2, v2, v3
	ds_bpermute_b32 v3, v55, v2
	s_waitcnt lgkmcnt(0)
	v_add_f32_e32 v13, v2, v3
	v_or_b32_e32 v2, v58, v28
	v_mul_u32_u24_e32 v2, 0xd00, v2
	v_lshlrev_b32_e32 v128, 1, v2
	v_lshl_add_u64 v[0:1], v[0:1], 0, v[128:129]
	v_mov_b64_e32 v[0:1], v[98:99]
	v_mov_b64_e32 v[2:3], v[100:101]
	v_cndmask_b32_e64 v58, v49, v50, s[38:39]
	v_lshlrev_b32_e32 v128, 4, v58
	v_lshl_add_u64 v[10:11], v[10:11], 0, v[128:129]
	global_store_dwordx4 v[10:11], v[0:3], off
	v_lshlrev_b32_e32 v10, 16, v0
	s_nop 0
	v_and_b32_e32 v0, 0xffff0000, v0
	v_mul_f32_e32 v0, v0, v0
	v_fmac_f32_e32 v0, v10, v10
	v_lshlrev_b32_e32 v10, 16, v1
	v_fmac_f32_e32 v0, v10, v10
	v_and_b32_e32 v1, 0xffff0000, v1
	v_fmac_f32_e32 v0, v1, v1
	v_lshlrev_b32_e32 v1, 16, v2
	v_fmac_f32_e32 v0, v1, v1
	v_and_b32_e32 v1, 0xffff0000, v2
	v_fmac_f32_e32 v0, v1, v1
	v_lshlrev_b32_e32 v1, 16, v3
	v_fmac_f32_e32 v0, v1, v1
	v_and_b32_e32 v1, 0xffff0000, v3
	v_fmac_f32_e32 v0, v1, v1
	ds_bpermute_b32 v1, v57, v0
	s_waitcnt lgkmcnt(0)
	v_add_f32_e32 v0, v0, v1
	ds_bpermute_b32 v1, v56, v0
	s_waitcnt lgkmcnt(0)
	v_add_f32_e32 v0, v0, v1
	ds_bpermute_b32 v1, v55, v0
	s_waitcnt lgkmcnt(0)
	v_add_f32_e32 v0, v0, v1
	v_xor_b32_e32 v1, 8, v197
	v_cmp_lt_i32_e64 s[0:1], v1, v54
	v_max3_f32 v0, v12, v13, v0
	s_nop 0
	v_cndmask_b32_e64 v1, v197, v1, s[0:1]
	v_lshlrev_b32_e32 v1, 2, v1
	ds_bpermute_b32 v1, v1, v0
	s_waitcnt lgkmcnt(0)
	v_max_f32_e32 v1, v1, v1
	v_max_f32_e32 v0, v0, v1
	v_xor_b32_e32 v1, 16, v197
	v_cmp_lt_i32_e64 s[0:1], v1, v54
	s_nop 1
	v_cndmask_b32_e64 v1, v197, v1, s[0:1]
	v_lshlrev_b32_e32 v1, 2, v1
	ds_bpermute_b32 v1, v1, v0
	s_waitcnt lgkmcnt(0)
	v_max_f32_e32 v1, v1, v1
	v_max_f32_e32 v0, v0, v1
	v_xor_b32_e32 v1, 32, v197
	v_cmp_lt_i32_e64 s[0:1], v1, v54
	s_nop 1
	v_cndmask_b32_e64 v1, v197, v1, s[0:1]
	v_lshlrev_b32_e32 v1, 2, v1
	ds_bpermute_b32 v1, v1, v0
	s_and_saveexec_b64 s[0:1], vcc
	s_cbranch_execz .LBB0_345
	v_lshrrev_b32_e32 v2, 22, v53
	v_add_u32_e32 v2, v52, v2
	v_ashrrev_i32_e32 v2, 10, v2
	s_waitcnt lgkmcnt(0)
	v_max_f32_e32 v1, v1, v1
	v_max_f32_e32 v0, v0, v0
	v_max_f32_e32 v3, v0, v1
	v_lshl_add_u32 v0, v2, 2, s8
	v_readlane_b32 s16, v252, 42
	v_ashrrev_i32_e32 v1, 31, v0
	v_readlane_b32 s17, v252, 43
	v_lshlrev_b32_e32 v128, 2, v9
	s_nop 0
	v_lshl_add_u64 v[0:1], v[0:1], 2, s[16:17]
	v_lshl_add_u64 v[0:1], v[0:1], 0, v[128:129]
	v_lshrrev_b32_e32 v2, 6, v185
	v_lshl_add_u32 v2, v2, 2, s44
	ds_write_b32 v2, v3
	s_waitcnt lgkmcnt(0)
	s_barrier
	s_mov_b32 s46, s44
	s_xor_b32 s44, s44, 32
	v_readfirstlane_b32 s45, v185
	s_nop 1
	s_lshr_b32 s45, s45, 6
	s_cmp_lg_u32 s45, 0
	s_cbranch_scc1 .LBB0_345
	v_mov_b32_e32 v2, s46
	ds_read_b128 v[108:111], v2
	ds_read_b128 v[112:115], v2 offset:16
	s_waitcnt lgkmcnt(0)
	v_max3_u32 v3, v108, v109, v110
	v_max3_u32 v3, v3, v111, v112
	v_max3_u32 v3, v3, v113, v114
	v_max_u32_e32 v3, v3, v115
	global_atomic_umax v[0:1], v3, off
	s_branch .LBB0_345
